# WO/F2 residual epilogue stores: write-through + nt streaming hint (sc1 nt)
# baseline (speedup 1.0000x reference)
.LBB0_43:
	s_lshl_b32 s3, s42, 8
	v_readlane_b32 s20, v252, 26
	s_add_i32 s20, s3, s20
	s_add_i32 s28, s20, 0xffff8000
	v_readlane_b32 s21, v252, 27
	s_lshr_b32 s28, s28, 13
	s_ashr_i32 s21, s20, 11
	s_add_i32 s28, s28, 16
	s_cmp_lt_i32 s20, 0x8000
	s_cselect_b32 s20, s21, s28
	v_add_u32_e32 v172, s3, v1
	v_lshl_or_b32 v98, s43, 8, v174
	s_mul_hi_i32 s21, s20, 0x6000
	s_mulk_i32 s20, 0x6000
	v_ashrrev_i32_e32 v173, 31, v172
	s_add_u32 s20, s45, s20
	v_ashrrev_i32_e32 v99, 31, v98
	v_lshlrev_b64 v[154:155], 12, v[172:173]
	s_addc_u32 s21, s82, s21
	v_lshlrev_b64 v[170:171], 2, v[98:99]
	v_lshl_add_u64 v[154:155], s[40:41], 0, v[154:155]
	v_lshl_add_u64 v[98:99], s[20:21], 0, v[170:171]
	v_lshl_add_u64 v[154:155], v[154:155], 0, v[170:171]
	global_load_dwordx4 v[130:133], v[98:99], off
	global_load_dwordx4 v[122:125], v[98:99], off offset:64
	global_load_dwordx4 v[114:117], v[98:99], off offset:512
	s_nop 0
	global_load_dwordx4 v[98:101], v[98:99], off offset:576
	s_mov_b32 s3, 0x80000
	v_lshl_add_u32 v248, v172, 12, v170
	s_add_u32 s20, s40, 0x0
	s_addc_u32 s21, s41, 0
	global_load_dwordx4 v[176:179], v248, s[20:21]
	global_load_dwordx4 v[180:183], v248, s[20:21] offset:64
	global_load_dwordx4 v[184:187], v248, s[20:21] offset:512
	global_load_dwordx4 v[188:191], v248, s[20:21] offset:576
	s_add_u32 s20, s40, 0x10000
	s_addc_u32 s21, s41, 0
	global_load_dwordx4 v[192:195], v248, s[20:21]
	global_load_dwordx4 v[196:199], v248, s[20:21] offset:64
	global_load_dwordx4 v[208:211], v248, s[20:21] offset:512
	global_load_dwordx4 v[212:215], v248, s[20:21] offset:576
	s_add_u32 s20, s40, 0x20000
	s_addc_u32 s21, s41, 0
	global_load_dwordx4 v[216:219], v248, s[20:21]
	global_load_dwordx4 v[220:223], v248, s[20:21] offset:64
	global_load_dwordx4 v[224:227], v248, s[20:21] offset:512
	global_load_dwordx4 v[228:231], v248, s[20:21] offset:576
	s_add_u32 s20, s40, 0x30000
	s_addc_u32 s21, s41, 0
	global_load_dwordx4 v[232:235], v248, s[20:21]
	global_load_dwordx4 v[236:239], v248, s[20:21] offset:64
	global_load_dwordx4 v[240:243], v248, s[20:21] offset:512
	global_load_dwordx4 v[244:247], v248, s[20:21] offset:576
	s_waitcnt vmcnt(12)
	v_pk_fma_f32 v[144:145], v[144:145], v[132:133], v[178:179]
	v_pk_fma_f32 v[142:143], v[142:143], v[130:131], v[176:177]
	v_pk_fma_f32 v[140:141], v[140:141], v[124:125], v[182:183]
	v_pk_fma_f32 v[138:139], v[138:139], v[122:123], v[180:181]
	v_pk_fma_f32 v[136:137], v[136:137], v[116:117], v[186:187]
	v_pk_fma_f32 v[134:135], v[134:135], v[114:115], v[184:185]
	v_pk_fma_f32 v[128:129], v[128:129], v[100:101], v[190:191]
	v_pk_fma_f32 v[126:127], v[126:127], v[98:99], v[188:189]
	s_add_u32 s48, s40, 0x0
	s_addc_u32 s49, s41, 0
	global_store_dwordx4 v248, v[142:145], s[48:49] sc1 nt
	global_store_dwordx4 v248, v[138:141], s[48:49] offset:64 sc1 nt
	global_store_dwordx4 v248, v[134:137], s[48:49] offset:512 sc1 nt
	global_store_dwordx4 v248, v[126:129], s[48:49] offset:576 sc1 nt
	s_add_u32 s20, s40, 0x80000
	s_addc_u32 s21, s41, 0
	global_load_dwordx4 v[176:179], v248, s[20:21]
	global_load_dwordx4 v[180:183], v248, s[20:21] offset:64
	global_load_dwordx4 v[184:187], v248, s[20:21] offset:512
	global_load_dwordx4 v[188:191], v248, s[20:21] offset:576
	s_waitcnt vmcnt(16)
	v_pk_fma_f32 v[120:121], v[120:121], v[132:133], v[194:195]
	v_pk_fma_f32 v[118:119], v[118:119], v[130:131], v[192:193]
	v_pk_fma_f32 v[112:113], v[112:113], v[124:125], v[198:199]
	v_pk_fma_f32 v[110:111], v[110:111], v[122:123], v[196:197]
	v_pk_fma_f32 v[108:109], v[108:109], v[116:117], v[210:211]
	v_pk_fma_f32 v[106:107], v[106:107], v[114:115], v[208:209]
	v_pk_fma_f32 v[104:105], v[104:105], v[100:101], v[214:215]
	v_pk_fma_f32 v[102:103], v[102:103], v[98:99], v[212:213]
	s_add_u32 s48, s40, 0x10000
	s_addc_u32 s49, s41, 0
	global_store_dwordx4 v248, v[118:121], s[48:49] sc1 nt
	global_store_dwordx4 v248, v[110:113], s[48:49] offset:64 sc1 nt
	global_store_dwordx4 v248, v[106:109], s[48:49] offset:512 sc1 nt
	global_store_dwordx4 v248, v[102:105], s[48:49] offset:576 sc1 nt
	s_add_u32 s20, s40, 0x90000
	s_addc_u32 s21, s41, 0
	global_load_dwordx4 v[192:195], v248, s[20:21]
	global_load_dwordx4 v[196:199], v248, s[20:21] offset:64
	global_load_dwordx4 v[208:211], v248, s[20:21] offset:512
	global_load_dwordx4 v[212:215], v248, s[20:21] offset:576
	s_waitcnt vmcnt(20)
	v_pk_fma_f32 v[96:97], v[96:97], v[132:133], v[218:219]
	v_pk_fma_f32 v[94:95], v[94:95], v[130:131], v[216:217]
	v_pk_fma_f32 v[92:93], v[92:93], v[124:125], v[222:223]
	v_pk_fma_f32 v[90:91], v[90:91], v[122:123], v[220:221]
	v_pk_fma_f32 v[88:89], v[88:89], v[116:117], v[226:227]
	v_pk_fma_f32 v[86:87], v[86:87], v[114:115], v[224:225]
	v_pk_fma_f32 v[84:85], v[84:85], v[100:101], v[230:231]
	v_pk_fma_f32 v[82:83], v[82:83], v[98:99], v[228:229]
	s_add_u32 s48, s40, 0x20000
	s_addc_u32 s49, s41, 0
	global_store_dwordx4 v248, v[94:97], s[48:49] sc1 nt
	global_store_dwordx4 v248, v[90:93], s[48:49] offset:64 sc1 nt
	global_store_dwordx4 v248, v[86:89], s[48:49] offset:512 sc1 nt
	global_store_dwordx4 v248, v[82:85], s[48:49] offset:576 sc1 nt
	s_add_u32 s20, s40, 0xa0000
	s_addc_u32 s21, s41, 0
	global_load_dwordx4 v[216:219], v248, s[20:21]
	global_load_dwordx4 v[220:223], v248, s[20:21] offset:64
	global_load_dwordx4 v[224:227], v248, s[20:21] offset:512
	global_load_dwordx4 v[228:231], v248, s[20:21] offset:576
	s_waitcnt vmcnt(24)
	v_pk_fma_f32 v[80:81], v[80:81], v[132:133], v[234:235]
	v_pk_fma_f32 v[78:79], v[78:79], v[130:131], v[232:233]
	v_pk_fma_f32 v[76:77], v[76:77], v[124:125], v[238:239]
	v_pk_fma_f32 v[74:75], v[74:75], v[122:123], v[236:237]
	v_pk_fma_f32 v[72:73], v[72:73], v[116:117], v[242:243]
	v_pk_fma_f32 v[70:71], v[70:71], v[114:115], v[240:241]
	v_pk_fma_f32 v[68:69], v[68:69], v[100:101], v[246:247]
	v_pk_fma_f32 v[66:67], v[66:67], v[98:99], v[244:245]
	s_add_u32 s48, s40, 0x30000
	s_addc_u32 s49, s41, 0
	global_store_dwordx4 v248, v[78:81], s[48:49] sc1 nt
	global_store_dwordx4 v248, v[74:77], s[48:49] offset:64 sc1 nt
	global_store_dwordx4 v248, v[70:73], s[48:49] offset:512 sc1 nt
	global_store_dwordx4 v248, v[66:69], s[48:49] offset:576 sc1 nt
	s_add_u32 s20, s40, 0xb0000
	s_addc_u32 s21, s41, 0
	global_load_dwordx4 v[232:235], v248, s[20:21]
	global_load_dwordx4 v[236:239], v248, s[20:21] offset:64
	global_load_dwordx4 v[240:243], v248, s[20:21] offset:512
	global_load_dwordx4 v[244:247], v248, s[20:21] offset:576
	s_waitcnt vmcnt(24)
	v_pk_fma_f32 v[64:65], v[64:65], v[132:133], v[178:179]
	v_pk_fma_f32 v[62:63], v[62:63], v[130:131], v[176:177]
	v_pk_fma_f32 v[60:61], v[60:61], v[124:125], v[182:183]
	v_pk_fma_f32 v[58:59], v[58:59], v[122:123], v[180:181]
	v_pk_fma_f32 v[56:57], v[56:57], v[116:117], v[186:187]
	v_pk_fma_f32 v[54:55], v[54:55], v[114:115], v[184:185]
	v_pk_fma_f32 v[52:53], v[52:53], v[100:101], v[190:191]
	v_pk_fma_f32 v[50:51], v[50:51], v[98:99], v[188:189]
	s_add_u32 s48, s40, 0x80000
	s_addc_u32 s49, s41, 0
	global_store_dwordx4 v248, v[62:65], s[48:49] sc1 nt
	global_store_dwordx4 v248, v[58:61], s[48:49] offset:64 sc1 nt
	global_store_dwordx4 v248, v[54:57], s[48:49] offset:512 sc1 nt
	global_store_dwordx4 v248, v[50:53], s[48:49] offset:576 sc1 nt
	s_waitcnt vmcnt(20)
	v_pk_fma_f32 v[48:49], v[48:49], v[132:133], v[194:195]
	v_pk_fma_f32 v[46:47], v[46:47], v[130:131], v[192:193]
	v_pk_fma_f32 v[44:45], v[44:45], v[124:125], v[198:199]
	v_pk_fma_f32 v[42:43], v[42:43], v[122:123], v[196:197]
	v_pk_fma_f32 v[40:41], v[40:41], v[116:117], v[210:211]
	v_pk_fma_f32 v[38:39], v[38:39], v[114:115], v[208:209]
	v_pk_fma_f32 v[36:37], v[36:37], v[100:101], v[214:215]
	v_pk_fma_f32 v[34:35], v[34:35], v[98:99], v[212:213]
	s_add_u32 s48, s40, 0x90000
	s_addc_u32 s49, s41, 0
	global_store_dwordx4 v248, v[46:49], s[48:49] sc1 nt
	global_store_dwordx4 v248, v[42:45], s[48:49] offset:64 sc1 nt
	global_store_dwordx4 v248, v[38:41], s[48:49] offset:512 sc1 nt
	global_store_dwordx4 v248, v[34:37], s[48:49] offset:576 sc1 nt
	s_waitcnt vmcnt(16)
	v_pk_fma_f32 v[32:33], v[32:33], v[132:133], v[218:219]
	v_pk_fma_f32 v[30:31], v[30:31], v[130:131], v[216:217]
	v_pk_fma_f32 v[28:29], v[28:29], v[124:125], v[222:223]
	v_pk_fma_f32 v[26:27], v[26:27], v[122:123], v[220:221]
	v_pk_fma_f32 v[24:25], v[24:25], v[116:117], v[226:227]
	v_pk_fma_f32 v[22:23], v[22:23], v[114:115], v[224:225]
	v_pk_fma_f32 v[20:21], v[20:21], v[100:101], v[230:231]
	v_pk_fma_f32 v[18:19], v[18:19], v[98:99], v[228:229]
	s_add_u32 s48, s40, 0xa0000
	s_addc_u32 s49, s41, 0
	global_store_dwordx4 v248, v[30:33], s[48:49] sc1 nt
	global_store_dwordx4 v248, v[26:29], s[48:49] offset:64 sc1 nt
	global_store_dwordx4 v248, v[22:25], s[48:49] offset:512 sc1 nt
	global_store_dwordx4 v248, v[18:21], s[48:49] offset:576 sc1 nt
	s_waitcnt vmcnt(12)
	v_pk_fma_f32 v[16:17], v[16:17], v[132:133], v[234:235]
	v_pk_fma_f32 v[14:15], v[14:15], v[130:131], v[232:233]
	v_pk_fma_f32 v[12:13], v[12:13], v[124:125], v[238:239]
	v_pk_fma_f32 v[10:11], v[10:11], v[122:123], v[236:237]
	v_pk_fma_f32 v[8:9], v[8:9], v[116:117], v[242:243]
	v_pk_fma_f32 v[6:7], v[6:7], v[114:115], v[240:241]
	v_pk_fma_f32 v[4:5], v[4:5], v[100:101], v[246:247]
	v_pk_fma_f32 v[2:3], v[2:3], v[98:99], v[244:245]
	s_add_u32 s48, s40, 0xb0000
	s_addc_u32 s49, s41, 0
	global_store_dwordx4 v248, v[14:17], s[48:49] sc1 nt
	global_store_dwordx4 v248, v[10:13], s[48:49] offset:64 sc1 nt
	global_store_dwordx4 v248, v[6:9], s[48:49] offset:512 sc1 nt
	global_store_dwordx4 v248, v[2:5], s[48:49] offset:576 sc1 nt
	s_mov_b64 s[20:21], -1
	s_and_b64 vcc, exec, s[36:37]
	s_cbranch_vccnz .LBB0_27
	v_readlane_b32 s20, v252, 38
	v_readlane_b32 s21, v252, 39
	s_andn2_b64 vcc, exec, s[20:21]
	s_cbranch_vccnz .LBB0_26
	s_barrier
	s_branch .LBB0_26

.LBB0_105:
	s_lshl_b32 s2, s2, 8
	v_readlane_b32 s20, v252, 26
	v_readlane_b32 s21, v252, 27
	s_add_i32 s13, s2, s20
	s_add_i32 s21, s13, 0xffff8000
	s_lshr_b32 s21, s21, 13
	s_ashr_i32 s20, s13, 11
	s_add_i32 s21, s21, 16
	s_cmp_lt_i32 s13, 0x8000
	v_add_u32_e32 v172, s2, v1
	v_lshl_or_b32 v170, s99, 8, v174
	s_cselect_b32 s13, s20, s21
	v_ashrrev_i32_e32 v173, 31, v172
	s_mul_hi_i32 s21, s13, 0x6000
	s_mulk_i32 s13, 0x6000
	v_ashrrev_i32_e32 v171, 31, v170
	v_lshlrev_b64 v[154:155], 10, v[172:173]
	s_add_u32 s20, s45, s13
	v_lshl_add_u64 v[154:155], v[154:155], 0, v[170:171]
	s_addc_u32 s21, s82, s21
	v_lshlrev_b64 v[154:155], 2, v[154:155]
	v_lshl_add_u64 v[130:131], v[170:171], 2, s[20:21]
	v_lshl_add_u64 v[180:181], s[30:31], 0, v[154:155]
	global_load_dwordx4 v[142:145], v[130:131], off
	global_load_dwordx4 v[138:141], v[130:131], off offset:64
	global_load_dwordx4 v[134:137], v[130:131], off offset:512
	s_nop 0
	global_load_dwordx4 v[130:133], v[130:131], off offset:576
	s_add_u32 s20, s30, 0x0
	s_addc_u32 s21, s31, 0
	global_load_dwordx4 v[176:179], v154, s[20:21]
	global_load_dwordx4 v[180:183], v154, s[20:21] offset:64
	global_load_dwordx4 v[184:187], v154, s[20:21] offset:512
	global_load_dwordx4 v[188:191], v154, s[20:21] offset:576
	s_add_u32 s20, s30, 0x10000
	s_addc_u32 s21, s31, 0
	global_load_dwordx4 v[192:195], v154, s[20:21]
	global_load_dwordx4 v[196:199], v154, s[20:21] offset:64
	global_load_dwordx4 v[208:211], v154, s[20:21] offset:512
	global_load_dwordx4 v[212:215], v154, s[20:21] offset:576
	s_add_u32 s20, s30, 0x20000
	s_addc_u32 s21, s31, 0
	global_load_dwordx4 v[216:219], v154, s[20:21]
	global_load_dwordx4 v[220:223], v154, s[20:21] offset:64
	global_load_dwordx4 v[224:227], v154, s[20:21] offset:512
	global_load_dwordx4 v[228:231], v154, s[20:21] offset:576
	s_add_u32 s20, s30, 0x30000
	s_addc_u32 s21, s31, 0
	global_load_dwordx4 v[232:235], v154, s[20:21]
	global_load_dwordx4 v[236:239], v154, s[20:21] offset:64
	global_load_dwordx4 v[240:243], v154, s[20:21] offset:512
	global_load_dwordx4 v[244:247], v154, s[20:21] offset:576
	s_waitcnt vmcnt(12)
	v_pk_fma_f32 v[128:129], v[128:129], v[144:145], v[178:179]
	v_pk_fma_f32 v[126:127], v[126:127], v[142:143], v[176:177]
	v_pk_fma_f32 v[124:125], v[124:125], v[140:141], v[182:183]
	v_pk_fma_f32 v[122:123], v[122:123], v[138:139], v[180:181]
	v_pk_fma_f32 v[120:121], v[120:121], v[136:137], v[186:187]
	v_pk_fma_f32 v[118:119], v[118:119], v[134:135], v[184:185]
	v_pk_fma_f32 v[116:117], v[116:117], v[132:133], v[190:191]
	v_pk_fma_f32 v[114:115], v[114:115], v[130:131], v[188:189]
	s_add_u32 s48, s40, 0x0
	s_addc_u32 s49, s41, 0
	global_store_dwordx4 v154, v[126:129], s[48:49] sc1 nt
	global_store_dwordx4 v154, v[122:125], s[48:49] offset:64 sc1 nt
	global_store_dwordx4 v154, v[118:121], s[48:49] offset:512 sc1 nt
	global_store_dwordx4 v154, v[114:117], s[48:49] offset:576 sc1 nt
	s_add_u32 s20, s30, 0x80000
	s_addc_u32 s21, s31, 0
	global_load_dwordx4 v[176:179], v154, s[20:21]
	global_load_dwordx4 v[180:183], v154, s[20:21] offset:64
	global_load_dwordx4 v[184:187], v154, s[20:21] offset:512
	global_load_dwordx4 v[188:191], v154, s[20:21] offset:576
	s_waitcnt vmcnt(16)
	v_pk_fma_f32 v[112:113], v[112:113], v[144:145], v[194:195]
	v_pk_fma_f32 v[110:111], v[110:111], v[142:143], v[192:193]
	v_pk_fma_f32 v[108:109], v[108:109], v[140:141], v[198:199]
	v_pk_fma_f32 v[106:107], v[106:107], v[138:139], v[196:197]
	v_pk_fma_f32 v[104:105], v[104:105], v[136:137], v[210:211]
	v_pk_fma_f32 v[102:103], v[102:103], v[134:135], v[208:209]
	v_pk_fma_f32 v[100:101], v[100:101], v[132:133], v[214:215]
	v_pk_fma_f32 v[98:99], v[98:99], v[130:131], v[212:213]
	s_add_u32 s48, s40, 0x10000
	s_addc_u32 s49, s41, 0
	global_store_dwordx4 v154, v[110:113], s[48:49] sc1 nt
	global_store_dwordx4 v154, v[106:109], s[48:49] offset:64 sc1 nt
	global_store_dwordx4 v154, v[102:105], s[48:49] offset:512 sc1 nt
	global_store_dwordx4 v154, v[98:101], s[48:49] offset:576 sc1 nt
	s_add_u32 s20, s30, 0x90000
	s_addc_u32 s21, s31, 0
	global_load_dwordx4 v[192:195], v154, s[20:21]
	global_load_dwordx4 v[196:199], v154, s[20:21] offset:64
	global_load_dwordx4 v[208:211], v154, s[20:21] offset:512
	global_load_dwordx4 v[212:215], v154, s[20:21] offset:576
	s_waitcnt vmcnt(20)
	v_pk_fma_f32 v[96:97], v[96:97], v[144:145], v[218:219]
	v_pk_fma_f32 v[94:95], v[94:95], v[142:143], v[216:217]
	v_pk_fma_f32 v[92:93], v[92:93], v[140:141], v[222:223]
	v_pk_fma_f32 v[90:91], v[90:91], v[138:139], v[220:221]
	v_pk_fma_f32 v[88:89], v[88:89], v[136:137], v[226:227]
	v_pk_fma_f32 v[86:87], v[86:87], v[134:135], v[224:225]
	v_pk_fma_f32 v[84:85], v[84:85], v[132:133], v[230:231]
	v_pk_fma_f32 v[82:83], v[82:83], v[130:131], v[228:229]
	s_add_u32 s48, s40, 0x20000
	s_addc_u32 s49, s41, 0
	global_store_dwordx4 v154, v[94:97], s[48:49] sc1 nt
	global_store_dwordx4 v154, v[90:93], s[48:49] offset:64 sc1 nt
	global_store_dwordx4 v154, v[86:89], s[48:49] offset:512 sc1 nt
	global_store_dwordx4 v154, v[82:85], s[48:49] offset:576 sc1 nt
	s_add_u32 s20, s30, 0xa0000
	s_addc_u32 s21, s31, 0
	global_load_dwordx4 v[216:219], v154, s[20:21]
	global_load_dwordx4 v[220:223], v154, s[20:21] offset:64
	global_load_dwordx4 v[224:227], v154, s[20:21] offset:512
	global_load_dwordx4 v[228:231], v154, s[20:21] offset:576
	s_waitcnt vmcnt(24)
	v_pk_fma_f32 v[80:81], v[80:81], v[144:145], v[234:235]
	v_pk_fma_f32 v[78:79], v[78:79], v[142:143], v[232:233]
	v_pk_fma_f32 v[76:77], v[76:77], v[140:141], v[238:239]
	v_pk_fma_f32 v[74:75], v[74:75], v[138:139], v[236:237]
	v_pk_fma_f32 v[72:73], v[72:73], v[136:137], v[242:243]
	v_pk_fma_f32 v[70:71], v[70:71], v[134:135], v[240:241]
	v_pk_fma_f32 v[68:69], v[68:69], v[132:133], v[246:247]
	v_pk_fma_f32 v[66:67], v[66:67], v[130:131], v[244:245]
	s_add_u32 s48, s40, 0x30000
	s_addc_u32 s49, s41, 0
	global_store_dwordx4 v154, v[78:81], s[48:49] sc1 nt
	global_store_dwordx4 v154, v[74:77], s[48:49] offset:64 sc1 nt
	global_store_dwordx4 v154, v[70:73], s[48:49] offset:512 sc1 nt
	global_store_dwordx4 v154, v[66:69], s[48:49] offset:576 sc1 nt
	s_add_u32 s20, s30, 0xb0000
	s_addc_u32 s21, s31, 0
	global_load_dwordx4 v[232:235], v154, s[20:21]
	global_load_dwordx4 v[236:239], v154, s[20:21] offset:64
	global_load_dwordx4 v[240:243], v154, s[20:21] offset:512
	global_load_dwordx4 v[244:247], v154, s[20:21] offset:576
	s_waitcnt vmcnt(24)
	v_pk_fma_f32 v[64:65], v[64:65], v[144:145], v[178:179]
	v_pk_fma_f32 v[62:63], v[62:63], v[142:143], v[176:177]
	v_pk_fma_f32 v[60:61], v[60:61], v[140:141], v[182:183]
	v_pk_fma_f32 v[58:59], v[58:59], v[138:139], v[180:181]
	v_pk_fma_f32 v[56:57], v[56:57], v[136:137], v[186:187]
	v_pk_fma_f32 v[54:55], v[54:55], v[134:135], v[184:185]
	v_pk_fma_f32 v[52:53], v[52:53], v[132:133], v[190:191]
	v_pk_fma_f32 v[50:51], v[50:51], v[130:131], v[188:189]
	s_add_u32 s48, s40, 0x80000
	s_addc_u32 s49, s41, 0
	global_store_dwordx4 v154, v[62:65], s[48:49] sc1 nt
	global_store_dwordx4 v154, v[58:61], s[48:49] offset:64 sc1 nt
	global_store_dwordx4 v154, v[54:57], s[48:49] offset:512 sc1 nt
	global_store_dwordx4 v154, v[50:53], s[48:49] offset:576 sc1 nt
	s_waitcnt vmcnt(20)
	v_pk_fma_f32 v[48:49], v[48:49], v[144:145], v[194:195]
	v_pk_fma_f32 v[46:47], v[46:47], v[142:143], v[192:193]
	v_pk_fma_f32 v[44:45], v[44:45], v[140:141], v[198:199]
	v_pk_fma_f32 v[42:43], v[42:43], v[138:139], v[196:197]
	v_pk_fma_f32 v[40:41], v[40:41], v[136:137], v[210:211]
	v_pk_fma_f32 v[38:39], v[38:39], v[134:135], v[208:209]
	v_pk_fma_f32 v[36:37], v[36:37], v[132:133], v[214:215]
	v_pk_fma_f32 v[34:35], v[34:35], v[130:131], v[212:213]
	s_add_u32 s48, s40, 0x90000
	s_addc_u32 s49, s41, 0
	global_store_dwordx4 v154, v[46:49], s[48:49] sc1 nt
	global_store_dwordx4 v154, v[42:45], s[48:49] offset:64 sc1 nt
	global_store_dwordx4 v154, v[38:41], s[48:49] offset:512 sc1 nt
	global_store_dwordx4 v154, v[34:37], s[48:49] offset:576 sc1 nt
	s_waitcnt vmcnt(16)
	v_pk_fma_f32 v[32:33], v[32:33], v[144:145], v[218:219]
	v_pk_fma_f32 v[30:31], v[30:31], v[142:143], v[216:217]
	v_pk_fma_f32 v[28:29], v[28:29], v[140:141], v[222:223]
	v_pk_fma_f32 v[26:27], v[26:27], v[138:139], v[220:221]
	v_pk_fma_f32 v[24:25], v[24:25], v[136:137], v[226:227]
	v_pk_fma_f32 v[22:23], v[22:23], v[134:135], v[224:225]
	v_pk_fma_f32 v[20:21], v[20:21], v[132:133], v[230:231]
	v_pk_fma_f32 v[18:19], v[18:19], v[130:131], v[228:229]
	s_add_u32 s48, s40, 0xa0000
	s_addc_u32 s49, s41, 0
	global_store_dwordx4 v154, v[30:33], s[48:49] sc1 nt
	global_store_dwordx4 v154, v[26:29], s[48:49] offset:64 sc1 nt
	global_store_dwordx4 v154, v[22:25], s[48:49] offset:512 sc1 nt
	global_store_dwordx4 v154, v[18:21], s[48:49] offset:576 sc1 nt
	s_waitcnt vmcnt(12)
	v_pk_fma_f32 v[16:17], v[16:17], v[144:145], v[234:235]
	v_pk_fma_f32 v[14:15], v[14:15], v[142:143], v[232:233]
	v_pk_fma_f32 v[12:13], v[12:13], v[140:141], v[238:239]
	v_pk_fma_f32 v[10:11], v[10:11], v[138:139], v[236:237]
	v_pk_fma_f32 v[8:9], v[8:9], v[136:137], v[242:243]
	v_pk_fma_f32 v[6:7], v[6:7], v[134:135], v[240:241]
	v_pk_fma_f32 v[4:5], v[4:5], v[132:133], v[246:247]
	v_pk_fma_f32 v[2:3], v[2:3], v[130:131], v[244:245]
	s_add_u32 s48, s40, 0xb0000
	s_addc_u32 s49, s41, 0
	global_store_dwordx4 v154, v[14:17], s[48:49] sc1 nt
	global_store_dwordx4 v154, v[10:13], s[48:49] offset:64 sc1 nt
	global_store_dwordx4 v154, v[6:9], s[48:49] offset:512 sc1 nt
	global_store_dwordx4 v154, v[2:5], s[48:49] offset:576 sc1 nt
	s_mov_b64 s[20:21], -1
	s_and_b64 vcc, exec, s[36:37]
	s_cbranch_vccnz .LBB0_89
	v_readlane_b32 s20, v252, 38
	v_readlane_b32 s21, v252, 39
	s_andn2_b64 vcc, exec, s[20:21]
	s_cbranch_vccnz .LBB0_88
	s_barrier
	s_branch .LBB0_88
